# mLSTM numerator buffer NB re-laid out lane-linear: pass1 stores and pass2 loads 1 KB-contiguous per instruction
# speedup vs baseline: 1.0217x; 1.0002x over previous
; #define LAS __attribute__((address_space(3)))
; __device__ __forceinline__ void mlstm_pass1(const bf16_t* PR, const bf16_t* QC, const bf16_t* KC, const float* Gt, const float* gain, bf16_t* Y, LAS unsigned char* lds, ...
;     ...
;             if (w < 4) { const LAS float* pk_ = (const LAS float*)(lds + ML_PARK + w * 8192) + lane;
; #pragma unroll
;                 for (int tt = 0; tt < 2; ++tt)
; #pragma unroll
;                     for (int e = 0; e < 16; ++e) res[tt][e] = pk_[tt * 1024 + e * 64]; }
;             {
;                 if (w < 4) {
; #pragma unroll
;                     for (int tt = 0; tt < 2; ++tt) { float* np = num_ptr(NB, r0 + 32 * tt + r, hm) + 32 * w + 4 * h;
; #pragma unroll
;                         for (int g4 = 0; g4 < 4; ++g4) *(f32x4*)(np + 8 * g4) = (f32x4){res[tt][4 * g4], res[tt][4 * g4 + 1], res[tt][4 * g4 + 2], res[tt][4 * g4 + 3]}; }
.LBB0_490:
	v_mov_b32_e32 v97, s3
	v_or_b32_e32 v96, s75, v142
	ds_read2st64_b32 v[64:65], v168 offset1:1
	ds_read2st64_b32 v[66:67], v168 offset0:2 offset1:3
	ds_read2st64_b32 v[68:69], v168 offset0:4 offset1:5
	ds_read2st64_b32 v[70:71], v168 offset0:6 offset1:7
	ds_read2st64_b32 v[72:73], v168 offset0:8 offset1:9
	ds_read2st64_b32 v[74:75], v168 offset0:10 offset1:11
	ds_read2st64_b32 v[76:77], v168 offset0:12 offset1:13
	ds_read2st64_b32 v[78:79], v168 offset0:14 offset1:15
	ds_read2st64_b32 v[80:81], v168 offset0:16 offset1:17
	ds_read2st64_b32 v[82:83], v168 offset0:18 offset1:19
	ds_read2st64_b32 v[84:85], v168 offset0:20 offset1:21
	ds_read2st64_b32 v[86:87], v168 offset0:22 offset1:23
	ds_read2st64_b32 v[88:89], v168 offset0:24 offset1:25
	ds_read2st64_b32 v[90:91], v168 offset0:26 offset1:27
	ds_read2st64_b32 v[92:93], v168 offset0:28 offset1:29
	ds_read2st64_b32 v[94:95], v168 offset0:30 offset1:31
	s_lshl_b32 s0, s90, 3
	s_add_i32 s0, s0, s91
	s_lshl_b32 s0, s0, 2
	s_add_i32 s0, s0, s93
	s_lshl_b32 s0, s0, 13
	v_readlane_b32 s98, v235, 2
	v_readlane_b32 s99, v235, 3
	s_nop 0
	s_add_u32 s98, s98, 0x4000000
	s_addc_u32 s99, s99, 0
	s_add_u32 s98, s98, s0
	s_addc_u32 s99, s99, 0
	v_mbcnt_lo_u32_b32 v204, -1, 0
	v_mbcnt_hi_u32_b32 v204, -1, v204
	v_lshlrev_b32_e32 v204, 4, v204
	s_waitcnt lgkmcnt(0)
	global_store_dwordx4 v204, v[64:67], s[98:99]
	global_store_dwordx4 v204, v[68:71], s[98:99] offset:1024
	global_store_dwordx4 v204, v[72:75], s[98:99] offset:2048
	global_store_dwordx4 v204, v[76:79], s[98:99] offset:3072
	s_add_u32 s98, s98, 0x1000
	s_addc_u32 s99, s99, 0
	global_store_dwordx4 v204, v[80:83], s[98:99]
	global_store_dwordx4 v204, v[84:87], s[98:99] offset:1024
	global_store_dwordx4 v204, v[88:91], s[98:99] offset:2048
	global_store_dwordx4 v204, v[92:95], s[98:99] offset:3072
	s_branch .LBB0_468

; __device__ __forceinline__ void mlstm_pass2(const bf16_t* PR, const bf16_t* QC, const float* gain, bf16_t* Y, LAS unsigned char* lds,
;                                             float* NB, const float* DEN, const float* BC, const float* FIMG, const float* DSEG, int st_first, int st_stride) {
;     ...
;         const size_t rs0 = (size_t)b * SEQL + 64 * (8 * seg);
;         const int frow = tid >> 4, fch = tid & 15;
;         const bf16_t* pQ = QC + (rs0 + frow) * 512 + hm * 128 + 8 * fch;
;         const int wq = (w < 4) ? w : 0;
;         const float* pN = num_ptr(NB, rs0 + r, hm) + 32 * wq + 4 * h;
;         const bf16_t* pO = PR + (rs0 + r) * PW + PC_OM + hm * 128 + 32 * wq + 4 * h;
;         const float* pB = BC + (rs0 + r) * 4 + hm; const float* pD = DEN + (rs0 + r) * 4 + hm;
;         f32x4 gv[4];
; #pragma unroll
;         for (int g4 = 0; g4 < 4; ++g4) gv[g4] = *(const f32x4*)(gain + hm * 128 + 32 * wq + 8 * g4 + 4 * h);
;         u32x4 fQ[2]; f32x4 nv[2][4]; u32x2 ov[2][4]; float bcv[2], dnv[2];
; #pragma unroll
;         for (int p2 = 0; p2 < 2; ++p2) fQ[p2] = *(const u32x4*)(pQ + (size_t)32 * p2 * 512);
; #pragma unroll
;         for (int tt = 0; tt < 2; ++tt) { bcv[tt] = pB[tt * 32 * 4]; dnv[tt] = pD[tt * 32 * 4];
; #pragma unroll
;             for (int g4 = 0; g4 < 4; ++g4) { nv[tt][g4] = *(const f32x4*)(pN + (size_t)tt * 32 * 512 + 8 * g4); ov[tt][g4] = *(const u32x2*)(pO + (size_t)tt * 32 * PW + 8 * g4); } }
.LBB0_570:
	s_cmp_lt_i32 s33, 4
	s_cselect_b32 s98, s33, 0
	s_lshl_b32 s99, s51, 5
	s_add_i32 s98, s98, s99
	s_lshl_b32 s98, s98, 13
	v_readlane_b32 s100, v235, 2
	v_readlane_b32 s101, v235, 3
	s_nop 0
	s_add_u32 s100, s100, 0x4000000
	s_addc_u32 s101, s101, 0
	s_add_u32 s100, s100, s98
	s_addc_u32 s101, s101, 0
	s_add_u32 s98, s100, 0x1000
	s_addc_u32 s99, s101, 0
	v_mbcnt_lo_u32_b32 v204, -1, 0
	v_mbcnt_hi_u32_b32 v204, -1, v204
	v_lshlrev_b32_e32 v204, 4, v204
	s_and_b32 s54, s8, 3
	s_ashr_i32 s8, s51, 4
	s_ashr_i32 s9, s8, 31
	s_lshl_b64 s[0:1], s[8:9], 11
	s_lshl_b32 s2, s26, 9
	s_or_b32 s2, s0, s2
	s_mov_b32 s3, s1
	v_lshl_add_u64 v[0:1], s[2:3], 0, v[110:111]
	v_mov_b32_e32 v3, s1
	v_or_b32_e32 v2, s2, v104
	v_lshlrev_b64 v[0:1], 10, v[0:1]
	v_lshlrev_b64 v[4:5], 11, v[2:3]
	v_mov_b64_e32 v[6:7], s[10:11]
	v_lshl_add_u64 v[0:1], s[12:13], 0, v[0:1]
	s_lshl_b32 s26, s54, 8
	v_lshl_add_u64 v[4:5], s[14:15], 0, v[4:5]
	s_lshl_b32 s40, s54, 9
	s_mov_b32 s41, s27
	v_mad_u64_u32 v[6:7], s[52:53], v2, s44, v[6:7]
	v_lshl_add_u64 v[0:1], v[0:1], 0, s[26:27]
	v_lshl_add_u64 v[4:5], v[4:5], 0, s[40:41]
	v_mad_i32_i24 v7, s1, v193, v7
	v_lshl_add_u64 v[10:11], v[114:115], 0, s[40:41]
	v_lshl_add_u64 v[4:5], s[28:29], 2, v[4:5]
	v_lshl_add_u64 v[6:7], v[6:7], 0, s[26:27]
	global_load_dwordx4 v[60:63], v[10:11], off
	global_load_dwordx4 v[56:59], v[10:11], off offset:32
	global_load_dwordx4 v[52:55], v[10:11], off offset:64
	global_load_dwordx4 v[48:51], v[10:11], off offset:96
	v_lshl_add_u64 v[0:1], v[0:1], 0, v[106:107]
	v_lshlrev_b32_e32 v10, 2, v112
	v_mov_b32_e32 v11, v107
	v_lshl_add_u64 v[6:7], s[28:29], 1, v[6:7]
	v_lshl_add_u64 v[4:5], v[4:5], 0, v[10:11]
	global_load_dwordx4 v[80:83], v[0:1], off
	v_add_co_u32_e32 v0, vcc, s45, v0
	v_lshlrev_b32_e32 v10, 1, v112
	s_nop 0
	v_addc_co_u32_e32 v1, vcc, 0, v1, vcc
	v_lshl_add_u64 v[6:7], v[6:7], 0, v[10:11]
	v_lshlrev_b64 v[2:3], 4, v[2:3]
	v_add_co_u32_e32 v12, vcc, s46, v6
	v_lshl_add_u64 v[8:9], s[16:17], 0, v[2:3]
	v_lshl_add_u64 v[2:3], s[18:19], 0, v[2:3]
	s_lshl_b32 s52, s54, 2
	s_mov_b32 s53, s27
	v_addc_co_u32_e32 v13, vcc, 0, v7, vcc
	v_lshl_add_u64 v[2:3], v[2:3], 0, s[52:53]
	v_lshl_add_u64 v[10:11], v[6:7], 0, s[30:31]
	v_lshl_add_u64 v[8:9], v[8:9], 0, s[52:53]
	global_load_dwordx2 v[186:187], v[12:13], off offset:2048
	global_load_dwordx4 v[100:103], v204, s[100:101]
	global_load_dwordx4 v[96:99], v204, s[100:101] offset:1024
	global_load_dwordx4 v[92:95], v204, s[100:101] offset:2048
	global_load_dwordx4 v[88:91], v204, s[100:101] offset:3072
	global_load_dword v198, v[8:9], off
	global_load_dwordx2 v[172:173], v[10:11], off offset:32
	global_load_dword v196, v[8:9], off offset:512
	global_load_dwordx2 v[170:171], v[10:11], off offset:48
	global_load_dwordx4 v[84:87], v[0:1], off
	global_load_dword v188, v[2:3], off
	global_load_dwordx2 v[174:175], v[10:11], off offset:16
	global_load_dword v197, v[2:3], off offset:512
	v_add_co_u32_e32 v0, vcc, s47, v4
	s_and_b32 s41, s50, 3
	s_nop 0
	v_addc_co_u32_e32 v1, vcc, 0, v5, vcc
	v_add_co_u32_e32 v2, vcc, s48, v6
	s_lshl_b32 s53, s41, 9
	s_nop 0
	v_addc_co_u32_e32 v3, vcc, 0, v7, vcc
	global_load_dwordx4 v[76:79], v204, s[98:99]
	global_load_dwordx4 v[72:75], v204, s[98:99] offset:1024
	global_load_dwordx4 v[68:71], v204, s[98:99] offset:2048
	global_load_dwordx4 v[64:67], v204, s[98:99] offset:3072
	global_load_dwordx2 v[168:169], v[2:3], off offset:2048
	global_load_dwordx2 v[166:167], v[2:3], off offset:2064
	global_load_dwordx2 v[164:165], v[2:3], off offset:2080
	global_load_dwordx2 v[162:163], v[2:3], off offset:2096
	s_lshl_b32 s54, s54, 7
	v_add_u32_e32 v160, s54, v119
	s_or_b32 s54, s0, s53
	s_mov_b32 s55, s1
	v_lshl_add_u64 v[0:1], s[54:55], 0, v[110:111]
	s_lshl_b32 s41, s41, 20
	v_lshlrev_b64 v[176:177], 10, v[0:1]
	s_lshl_b64 s[8:9], s[8:9], 22
	v_or_b32_e32 v0, v116, v176
	s_or_b32 s8, s8, s41
	v_ashrrev_i32_e32 v161, 31, v160
	v_or_b32_e32 v176, s26, v0
	v_mov_b32_e32 v0, s8
	v_mov_b32_e32 v1, s9
	v_lshl_add_u64 v[0:1], v[160:161], 1, v[0:1]
	v_lshl_add_u64 v[178:179], v[122:123], 0, v[0:1]
	v_or_b32_e32 v0, s0, v104
	v_mov_b32_e32 v1, s1
	v_or_b32_e32 v0, s53, v0
	v_lshlrev_b64 v[2:3], 11, v[0:1]
	v_lshlrev_b64 v[182:183], 4, v[0:1]
	v_mad_u64_u32 v[0:1], s[8:9], v0, s44, v[126:127]
	v_or_b32_e32 v2, s40, v2
	v_mad_i32_i24 v1, s1, v193, v1
	v_lshl_add_u64 v[180:181], v[124:125], 0, v[2:3]
	v_or_b32_e32 v182, s52, v182
	v_lshl_add_u64 v[184:185], v[0:1], 0, s[26:27]
	s_mov_b64 s[0:1], 0
	s_waitcnt vmcnt(0)
	s_branch .LBB0_572

; __device__ __forceinline__ float sigmoid_f(float x) { return __builtin_amdgcn_rcpf(1.f + __builtin_amdgcn_exp2f(-x * LOG2E)); }
; __device__ __forceinline__ void mlstm_pass2(const bf16_t* PR, const bf16_t* QC, const float* gain, bf16_t* Y, LAS unsigned char* lds,
;                                             float* NB, const float* DEN, const float* BC, const float* FIMG, const float* DSEG, int st_first, int st_stride) {
;     ...
;             if (cc < 7) { pN += (size_t)64 * 512; pB += 64 * 4; pD += 64 * 4;
; #pragma unroll
;                 for (int tt = 0; tt < 2; ++tt) { bcv[tt] = pB[tt * 32 * 4]; dnv[tt] = pD[tt * 32 * 4];
; #pragma unroll
;                     for (int g4 = 0; g4 < 4; ++g4) nv[tt][g4] = *(const f32x4*)(pN + (size_t)tt * 32 * 512 + 8 * g4); } }
;             __syncthreads();
;             if (w < 4) {
; #pragma unroll
;                 for (int tt = 0; tt < 2; ++tt) {
;                     const float dd = 1.f / fmaxf(fabsf(den_t[32 * tt + r]), 1.f); float ss = 0.f;
; #pragma unroll
;                     for (int g4 = 0; g4 < 4; ++g4) { const u32x2 o2 = ov[tt][g4];
;                         const float og[4] = {__uint_as_float(o2.x << 16), __uint_as_float(o2.x & 0xffff0000u), __uint_as_float(o2.y << 16), __uint_as_float(o2.y & 0xffff0000u)};
; #pragma unroll
;                         for (int e = 0; e < 4; ++e) { const float v = res[tt][4 * g4 + e] * dd * sigmoid_f(og[e]); res[tt][4 * g4 + e] = v; ss += v * v; } }
;                     ss += __shfl_xor(ss, 32);
;                     if (h == 0) ssq_t[64 * w + 32 * tt + r] = ss;
;                 }
.LBB0_585:
	s_nop 8
	v_lshl_add_u64 v[2:3], s[10:11], 0, v[182:183]
	v_add_co_u32_e32 v4, vcc, 0x1d400000, v2
	v_lshl_add_u64 v[0:1], v[180:181], 0, s[0:1]
	s_nop 0
	v_addc_co_u32_e32 v5, vcc, 0, v3, vcc
	v_add_co_u32_e32 v2, vcc, 0x1d300000, v2
	s_nop 1
	v_addc_co_u32_e32 v3, vcc, 0, v3, vcc
	v_add_co_u32_e32 v6, vcc, 0x4020000, v0
	s_nop 1
	v_addc_co_u32_e32 v7, vcc, 0, v1, vcc
	s_lshr_b32 s98, s0, 2
	s_add_u32 s98, s98, 0x8000
	s_add_u32 s98, s100, s98
	s_addc_u32 s99, s101, 0
	global_load_dwordx4 v[100:103], v204, s[98:99]
	global_load_dwordx4 v[96:99], v204, s[98:99] offset:1024
	global_load_dwordx4 v[92:95], v204, s[98:99] offset:2048
	global_load_dwordx4 v[88:91], v204, s[98:99] offset:3072
	global_load_dword v188, v[4:5], off offset:1024
	global_load_dword v198, v[2:3], off offset:1024
	global_load_dword v196, v[2:3], off offset:1536
	global_load_dword v197, v[4:5], off offset:1536
	v_add_co_u32_e32 v0, vcc, 0x4030000, v0
	s_nop 1
	v_addc_co_u32_e32 v1, vcc, 0, v1, vcc
	s_add_u32 s98, s98, 0x1000
	s_addc_u32 s99, s99, 0
	global_load_dwordx4 v[76:79], v204, s[98:99]
	global_load_dwordx4 v[72:75], v204, s[98:99] offset:1024
	global_load_dwordx4 v[68:71], v204, s[98:99] offset:2048
	global_load_dwordx4 v[64:67], v204, s[98:99] offset:3072
	v_cndmask_b32_e64 v0, 0, 1, s[24:25]
	v_cmp_ne_u32_e64 s[8:9], 1, v0
	s_andn2_b64 vcc, exec, s[24:25]
	s_waitcnt lgkmcnt(0)
	s_barrier
	s_cbranch_vccnz .LBB0_591
	ds_read_b32 v0, v105 offset:62720
	v_and_b32_e32 v2, 64, v195
	v_xor_b32_e32 v1, 32, v195
	v_add_u32_e32 v2, 64, v2
	v_cmp_lt_i32_e32 vcc, v1, v2
	s_waitcnt lgkmcnt(0)
	v_max_f32_e64 v0, |v0|, |v0|
	v_max_f32_e32 v3, 1.0, v0
	v_div_scale_f32 v4, s[40:41], v3, v3, 1.0
	v_rcp_f32_e32 v5, v4
	v_cndmask_b32_e32 v0, v195, v1, vcc
	v_and_b32_e32 v7, 0xffff0000, v187
	v_lshlrev_b32_e32 v10, 16, v175
	v_fma_f32 v1, -v4, v5, 1.0
	v_fmac_f32_e32 v5, v1, v5
	v_div_scale_f32 v1, vcc, 1.0, v3, 1.0
	v_mul_f32_e32 v2, v1, v5
	v_fma_f32 v6, -v4, v2, v1
	v_fmac_f32_e32 v2, v6, v5
	v_fma_f32 v1, -v4, v2, v1
	v_div_fmas_f32 v1, v1, v5, v2
	v_div_fixup_f32 v2, v1, v3, 1.0
	v_lshlrev_b32_e32 v1, 16, v186
	v_and_b32_e32 v3, 0xffff0000, v186
	v_mul_f32_e32 v1, 0xbfb8aa3b, v1
	v_exp_f32_e32 v1, v1
	v_mul_f32_e32 v3, 0xbfb8aa3b, v3
	v_exp_f32_e32 v3, v3
	v_lshlrev_b32_e32 v6, 16, v187
	v_add_f32_e32 v1, 1.0, v1
	v_rcp_f32_e32 v4, v1
	v_add_f32_e32 v1, 1.0, v3
	v_rcp_f32_e32 v5, v1
	v_mul_f32_e32 v1, 0xbfb8aa3b, v6
	v_exp_f32_e32 v1, v1
	v_mul_f32_e32 v3, 0xbfb8aa3b, v7
	v_exp_f32_e32 v3, v3
	v_and_b32_e32 v11, 0xffff0000, v175
	v_add_f32_e32 v1, 1.0, v1
	v_rcp_f32_e32 v8, v1
	v_add_f32_e32 v1, 1.0, v3
	v_pk_mul_f32 v[6:7], v[128:129], v[2:3] op_sel_hi:[1,0]
	v_rcp_f32_e32 v9, v1
	v_lshlrev_b32_e32 v1, 16, v174
	v_pk_mul_f32 v[128:129], v[4:5], v[6:7]
	v_pk_mul_f32 v[6:7], v[130:131], v[2:3] op_sel_hi:[1,0]
	v_and_b32_e32 v3, 0xffff0000, v174
	v_mul_f32_e32 v1, 0xbfb8aa3b, v1
	v_exp_f32_e32 v1, v1
	v_mul_f32_e32 v3, 0xbfb8aa3b, v3
	v_exp_f32_e32 v3, v3
	v_pk_mul_f32 v[130:131], v[8:9], v[6:7]
	v_add_f32_e32 v1, 1.0, v1
	v_rcp_f32_e32 v8, v1
	v_add_f32_e32 v1, 1.0, v3
	v_rcp_f32_e32 v9, v1
	v_mul_f32_e32 v1, 0xbfb8aa3b, v10
	v_exp_f32_e32 v1, v1
	v_mul_f32_e32 v3, 0xbfb8aa3b, v11
	v_exp_f32_e32 v3, v3
	v_lshlrev_b32_e32 v14, 16, v173
	v_add_f32_e32 v1, 1.0, v1
	v_rcp_f32_e32 v12, v1
	v_add_f32_e32 v1, 1.0, v3
	v_pk_mul_f32 v[10:11], v[136:137], v[2:3] op_sel_hi:[1,0]
	v_rcp_f32_e32 v13, v1
	v_lshlrev_b32_e32 v1, 16, v172
	v_pk_mul_f32 v[136:137], v[8:9], v[10:11]
	v_pk_mul_f32 v[10:11], v[142:143], v[2:3] op_sel_hi:[1,0]
	v_and_b32_e32 v3, 0xffff0000, v172
	v_mul_f32_e32 v1, 0xbfb8aa3b, v1
	v_exp_f32_e32 v1, v1
	v_mul_f32_e32 v3, 0xbfb8aa3b, v3
	v_exp_f32_e32 v3, v3
	v_pk_mul_f32 v[142:143], v[12:13], v[10:11]
	v_add_f32_e32 v1, 1.0, v1
	v_rcp_f32_e32 v12, v1
	v_add_f32_e32 v1, 1.0, v3
	v_and_b32_e32 v15, 0xffff0000, v173
	v_rcp_f32_e32 v13, v1
	v_mul_f32_e32 v1, 0xbfb8aa3b, v14
	v_exp_f32_e32 v1, v1
	v_mul_f32_e32 v3, 0xbfb8aa3b, v15
	v_exp_f32_e32 v3, v3
	v_pk_mul_f32 v[4:5], v[128:129], v[128:129]
	v_add_f32_e32 v1, 1.0, v1
	v_rcp_f32_e32 v172, v1
	v_add_f32_e32 v1, 1.0, v3
	v_pk_mul_f32 v[14:15], v[148:149], v[2:3] op_sel_hi:[1,0]
	v_rcp_f32_e32 v173, v1
	v_lshlrev_b32_e32 v1, 16, v170
	v_pk_mul_f32 v[148:149], v[12:13], v[14:15]
	v_pk_mul_f32 v[14:15], v[154:155], v[2:3] op_sel_hi:[1,0]
	v_and_b32_e32 v3, 0xffff0000, v170
	v_mul_f32_e32 v1, 0xbfb8aa3b, v1
	v_exp_f32_e32 v1, v1
	v_mul_f32_e32 v3, 0xbfb8aa3b, v3
	v_exp_f32_e32 v3, v3
	v_pk_mul_f32 v[154:155], v[172:173], v[14:15]
	v_add_f32_e32 v1, 1.0, v1
	v_lshlrev_b32_e32 v172, 16, v171
	v_rcp_f32_e32 v170, v1
	v_add_f32_e32 v1, 1.0, v3
	v_and_b32_e32 v173, 0xffff0000, v171
	v_rcp_f32_e32 v171, v1
	v_mul_f32_e32 v1, 0xbfb8aa3b, v172
	v_exp_f32_e32 v1, v1
	v_mul_f32_e32 v3, 0xbfb8aa3b, v173
	v_exp_f32_e32 v3, v3
	v_pk_mul_f32 v[6:7], v[130:131], v[130:131]
	v_add_f32_e32 v1, 1.0, v1
	v_rcp_f32_e32 v172, v1
	v_add_f32_e32 v1, 1.0, v3
	v_rcp_f32_e32 v173, v1
	v_add_f32_e32 v1, v4, v5
	v_add_f32_e32 v1, v6, v1
	v_pk_mul_f32 v[8:9], v[136:137], v[136:137]
	v_add_f32_e32 v1, v7, v1
	v_add_f32_e32 v1, v8, v1
	v_pk_mul_f32 v[10:11], v[142:143], v[142:143]
	v_add_f32_e32 v1, v9, v1
	v_add_f32_e32 v1, v10, v1
	v_pk_mul_f32 v[12:13], v[148:149], v[148:149]
	v_add_f32_e32 v1, v11, v1
	v_add_f32_e32 v1, v12, v1
	v_pk_mul_f32 v[14:15], v[154:155], v[154:155]
	v_pk_mul_f32 v[156:157], v[156:157], v[2:3] op_sel_hi:[1,0]
	v_add_f32_e32 v1, v13, v1
	v_pk_mul_f32 v[156:157], v[170:171], v[156:157]
	v_add_f32_e32 v1, v14, v1
	v_pk_mul_f32 v[170:171], v[156:157], v[156:157]
	v_pk_mul_f32 v[2:3], v[158:159], v[2:3] op_sel_hi:[1,0]
	v_add_f32_e32 v1, v15, v1
	v_pk_mul_f32 v[158:159], v[172:173], v[2:3]
	v_add_f32_e32 v1, v170, v1
	v_pk_mul_f32 v[2:3], v[158:159], v[158:159]
	v_add_f32_e32 v1, v171, v1
	v_add_f32_e32 v1, v2, v1
	v_lshlrev_b32_e32 v0, 2, v0
	v_add_f32_e32 v1, v3, v1
	ds_bpermute_b32 v2, v0, v1
	s_and_saveexec_b64 s[40:41], s[4:5]
	s_cbranch_execz .LBB0_588
	s_waitcnt lgkmcnt(0)
	v_add_f32_e32 v1, v1, v2
	ds_write_b32 v117, v1 offset:62976
